# layer 0 reads residual stream directly from input x: prologue x->out copy removed
# speedup vs baseline: 1.0151x; 1.0003x over previous
;     __device__ __forceinline__ void operator()(const f32x4 (&acc)[2][2][4][2], const pg8::Unit& u, int wr, int wc, int fr, int fq) const {
;     ...
;         float* xb = u.pm < 64 ? XL : (XC - (size_t)ML * DM);
;         const ptrdiff_t pboff = split ? (PB + (size_t)u.part * MC * DM) - XC : 0;
;         const float* gp = gate + mi * 6144 + col0;
;         f32x4 gv[2][2];
; #pragma unroll
;         for (int bj = 0; bj < 2; ++bj)
; #pragma unroll
;             for (int n = 0; n < 2; ++n) gv[bj][n] = *(const f32x4*)(gp + bj * 128 + n * 16) * gs;
; #pragma unroll
;         for (int ai = 0; ai < 2; ++ai)
; #pragma unroll
;             for (int m = 0; m < 4; ++m) {
;                 float* rowp = xb + (size_t)(row0 + ai * 128 + m * 16) * DM + col0;
; #pragma unroll
;                 for (int bj = 0; bj < 2; ++bj)
; #pragma unroll
;                     for (int n = 0; n < 2; ++n) {
;                         const f32x4 v = gv[bj][n] * acc[ai][bj][m][n]; float* pe = rowp + bj * 128 + n * 16;
;                         if (split) *(f32x4*)(pe + pboff) = v;
;                         else { f32x4* p = (f32x4*)pe; *p = *p + v; }
.Lres16_rmw:
	s_mov_b64 s[2:3], s[4:5]
	s_cmp_lg_u32 s29, 6
	s_cbranch_scc1 .Lres16_ld
	s_load_dwordx2 s[2:3], s[90:91], 0x0
	s_waitcnt lgkmcnt(0)

;     __device__ __forceinline__ void operator()(const f32x4 (&acc)[2][2][4][2], const pg8::Unit& u, int wr, int wc, int fr, int fq) const {
;     ...
;                         const f32x4 v = gv[bj][n] * acc[ai][bj][m][n]; float* pe = rowp + bj * 128 + n * 16;
;                         if (split) *(f32x4*)(pe + pboff) = v;
;                         else { f32x4* p = (f32x4*)pe; *p = *p + v; }
.Lres16_ld:
	global_load_dwordx4 v[162:165], v150, s[2:3]
	global_load_dwordx4 v[166:169], v150, s[2:3] offset:64
	global_load_dwordx4 v[170:173], v150, s[2:3] offset:512
	global_load_dwordx4 v[174:177], v150, s[2:3] offset:576
	global_load_dwordx4 v[184:187], v151, s[2:3]
	global_load_dwordx4 v[188:191], v151, s[2:3] offset:64
	global_load_dwordx4 v[204:207], v151, s[2:3] offset:512
	global_load_dwordx4 v[210:213], v151, s[2:3] offset:576
	global_load_dwordx4 v[214:217], v152, s[2:3]
	global_load_dwordx4 v[218:221], v152, s[2:3] offset:64
	global_load_dwordx4 v[222:225], v152, s[2:3] offset:512
	global_load_dwordx4 v[228:231], v152, s[2:3] offset:576
	global_load_dwordx4 v[232:235], v153, s[2:3]
	global_load_dwordx4 v[236:239], v153, s[2:3] offset:64
	global_load_dwordx4 v[240:243], v153, s[2:3] offset:512
	global_load_dwordx4 v[244:247], v153, s[2:3] offset:576
	s_waitcnt vmcnt(15)
	v_pk_add_f32 v[142:143], v[142:143], v[164:165]
	v_pk_add_f32 v[140:141], v[140:141], v[162:163]

;     __device__ __forceinline__ void operator()(const f32x4 (&acc)[2][2][4][2], const pg8::Unit& u, int wr, int wc, int fr, int fq) const {
;     ...
;                         const f32x4 v = gv[bj][n] * acc[ai][bj][m][n]; float* pe = rowp + bj * 128 + n * 16;
;                         if (split) *(f32x4*)(pe + pboff) = v;
;                         else { f32x4* p = (f32x4*)pe; *p = *p + v; }
	global_store_dwordx4 v150, v[140:143], s[4:5]
	s_waitcnt vmcnt(15)
	v_pk_add_f32 v[138:139], v[138:139], v[168:169]
	v_pk_add_f32 v[136:137], v[136:137], v[166:167]

;     __device__ __forceinline__ void operator()(const f32x4 (&acc)[2][2][4][2], const pg8::Unit& u, int wr, int wc, int fr, int fq) const {
;     ...
;                         const f32x4 v = gv[bj][n] * acc[ai][bj][m][n]; float* pe = rowp + bj * 128 + n * 16;
;                         if (split) *(f32x4*)(pe + pboff) = v;
;                         else { f32x4* p = (f32x4*)pe; *p = *p + v; }
	global_store_dwordx4 v150, v[136:139], s[4:5] offset:64
	s_waitcnt vmcnt(15)
	v_pk_add_f32 v[134:135], v[134:135], v[172:173]
	v_pk_add_f32 v[132:133], v[132:133], v[170:171]

;     __device__ __forceinline__ void operator()(const f32x4 (&acc)[2][2][4][2], const pg8::Unit& u, int wr, int wc, int fr, int fq) const {
;     ...
;                         const f32x4 v = gv[bj][n] * acc[ai][bj][m][n]; float* pe = rowp + bj * 128 + n * 16;
;                         if (split) *(f32x4*)(pe + pboff) = v;
;                         else { f32x4* p = (f32x4*)pe; *p = *p + v; }
	global_store_dwordx4 v150, v[132:135], s[4:5] offset:512
	s_waitcnt vmcnt(15)
	v_pk_add_f32 v[130:131], v[130:131], v[176:177]
	v_pk_add_f32 v[128:129], v[128:129], v[174:175]

;     __device__ __forceinline__ void operator()(const f32x4 (&acc)[2][2][4][2], const pg8::Unit& u, int wr, int wc, int fr, int fq) const {
;     ...
;                         const f32x4 v = gv[bj][n] * acc[ai][bj][m][n]; float* pe = rowp + bj * 128 + n * 16;
;                         if (split) *(f32x4*)(pe + pboff) = v;
;                         else { f32x4* p = (f32x4*)pe; *p = *p + v; }
	global_store_dwordx4 v150, v[128:131], s[4:5] offset:576
	s_waitcnt vmcnt(15)
	v_pk_add_f32 v[126:127], v[126:127], v[186:187]
	v_pk_add_f32 v[124:125], v[124:125], v[184:185]

;     __device__ __forceinline__ void operator()(const f32x4 (&acc)[2][2][4][2], const pg8::Unit& u, int wr, int wc, int fr, int fq) const {
;     ...
;                         const f32x4 v = gv[bj][n] * acc[ai][bj][m][n]; float* pe = rowp + bj * 128 + n * 16;
;                         if (split) *(f32x4*)(pe + pboff) = v;
;                         else { f32x4* p = (f32x4*)pe; *p = *p + v; }
	global_store_dwordx4 v151, v[124:127], s[4:5]
	s_waitcnt vmcnt(15)
	v_pk_add_f32 v[122:123], v[122:123], v[190:191]
	v_pk_add_f32 v[120:121], v[120:121], v[188:189]

;     __device__ __forceinline__ void operator()(const f32x4 (&acc)[2][2][4][2], const pg8::Unit& u, int wr, int wc, int fr, int fq) const {
;     ...
;                         const f32x4 v = gv[bj][n] * acc[ai][bj][m][n]; float* pe = rowp + bj * 128 + n * 16;
;                         if (split) *(f32x4*)(pe + pboff) = v;
;                         else { f32x4* p = (f32x4*)pe; *p = *p + v; }
	global_store_dwordx4 v151, v[120:123], s[4:5] offset:64
	s_waitcnt vmcnt(15)
	v_pk_add_f32 v[118:119], v[118:119], v[206:207]
	v_pk_add_f32 v[116:117], v[116:117], v[204:205]

;     __device__ __forceinline__ void operator()(const f32x4 (&acc)[2][2][4][2], const pg8::Unit& u, int wr, int wc, int fr, int fq) const {
;     ...
;                         const f32x4 v = gv[bj][n] * acc[ai][bj][m][n]; float* pe = rowp + bj * 128 + n * 16;
;                         if (split) *(f32x4*)(pe + pboff) = v;
;                         else { f32x4* p = (f32x4*)pe; *p = *p + v; }
	global_store_dwordx4 v151, v[116:119], s[4:5] offset:512
	s_waitcnt vmcnt(15)
	v_pk_add_f32 v[114:115], v[114:115], v[212:213]
	v_pk_add_f32 v[112:113], v[112:113], v[210:211]

;     __device__ __forceinline__ void operator()(const f32x4 (&acc)[2][2][4][2], const pg8::Unit& u, int wr, int wc, int fr, int fq) const {
;     ...
;                         const f32x4 v = gv[bj][n] * acc[ai][bj][m][n]; float* pe = rowp + bj * 128 + n * 16;
;                         if (split) *(f32x4*)(pe + pboff) = v;
;                         else { f32x4* p = (f32x4*)pe; *p = *p + v; }
	global_store_dwordx4 v151, v[112:115], s[4:5] offset:576
	s_waitcnt vmcnt(15)
	v_pk_add_f32 v[110:111], v[110:111], v[216:217]
	v_pk_add_f32 v[108:109], v[108:109], v[214:215]

;     __device__ __forceinline__ void operator()(const f32x4 (&acc)[2][2][4][2], const pg8::Unit& u, int wr, int wc, int fr, int fq) const {
;     ...
;                         const f32x4 v = gv[bj][n] * acc[ai][bj][m][n]; float* pe = rowp + bj * 128 + n * 16;
;                         if (split) *(f32x4*)(pe + pboff) = v;
;                         else { f32x4* p = (f32x4*)pe; *p = *p + v; }
	global_store_dwordx4 v152, v[108:111], s[4:5]
	s_waitcnt vmcnt(15)
	v_pk_add_f32 v[106:107], v[106:107], v[220:221]
	v_pk_add_f32 v[104:105], v[104:105], v[218:219]

;     __device__ __forceinline__ void operator()(const f32x4 (&acc)[2][2][4][2], const pg8::Unit& u, int wr, int wc, int fr, int fq) const {
;     ...
;                         const f32x4 v = gv[bj][n] * acc[ai][bj][m][n]; float* pe = rowp + bj * 128 + n * 16;
;                         if (split) *(f32x4*)(pe + pboff) = v;
;                         else { f32x4* p = (f32x4*)pe; *p = *p + v; }
	global_store_dwordx4 v152, v[104:107], s[4:5] offset:64
	s_waitcnt vmcnt(15)
	v_pk_add_f32 v[98:99], v[98:99], v[224:225]
	v_pk_add_f32 v[96:97], v[96:97], v[222:223]

;     __device__ __forceinline__ void operator()(const f32x4 (&acc)[2][2][4][2], const pg8::Unit& u, int wr, int wc, int fr, int fq) const {
;     ...
;                         const f32x4 v = gv[bj][n] * acc[ai][bj][m][n]; float* pe = rowp + bj * 128 + n * 16;
;                         if (split) *(f32x4*)(pe + pboff) = v;
;                         else { f32x4* p = (f32x4*)pe; *p = *p + v; }
	global_store_dwordx4 v152, v[96:99], s[4:5] offset:512
	s_waitcnt vmcnt(15)
	v_pk_add_f32 v[90:91], v[90:91], v[230:231]
	v_pk_add_f32 v[88:89], v[88:89], v[228:229]

;     __device__ __forceinline__ void operator()(const f32x4 (&acc)[2][2][4][2], const pg8::Unit& u, int wr, int wc, int fr, int fq) const {
;     ...
;                         const f32x4 v = gv[bj][n] * acc[ai][bj][m][n]; float* pe = rowp + bj * 128 + n * 16;
;                         if (split) *(f32x4*)(pe + pboff) = v;
;                         else { f32x4* p = (f32x4*)pe; *p = *p + v; }
	global_store_dwordx4 v152, v[88:91], s[4:5] offset:576
	s_waitcnt vmcnt(15)
	v_pk_add_f32 v[82:83], v[82:83], v[234:235]
	v_pk_add_f32 v[80:81], v[80:81], v[232:233]

;     __device__ __forceinline__ void operator()(const f32x4 (&acc)[2][2][4][2], const pg8::Unit& u, int wr, int wc, int fr, int fq) const {
;     ...
;                         const f32x4 v = gv[bj][n] * acc[ai][bj][m][n]; float* pe = rowp + bj * 128 + n * 16;
;                         if (split) *(f32x4*)(pe + pboff) = v;
;                         else { f32x4* p = (f32x4*)pe; *p = *p + v; }
	global_store_dwordx4 v153, v[80:83], s[4:5]
	s_waitcnt vmcnt(15)
	v_pk_add_f32 v[74:75], v[74:75], v[238:239]
	v_pk_add_f32 v[72:73], v[72:73], v[236:237]

;     __device__ __forceinline__ void operator()(const f32x4 (&acc)[2][2][4][2], const pg8::Unit& u, int wr, int wc, int fr, int fq) const {
;     ...
;                         const f32x4 v = gv[bj][n] * acc[ai][bj][m][n]; float* pe = rowp + bj * 128 + n * 16;
;                         if (split) *(f32x4*)(pe + pboff) = v;
;                         else { f32x4* p = (f32x4*)pe; *p = *p + v; }
	global_store_dwordx4 v153, v[72:75], s[4:5] offset:64
	s_waitcnt vmcnt(15)
	v_pk_add_f32 v[70:71], v[70:71], v[242:243]
	v_pk_add_f32 v[68:69], v[68:69], v[240:241]

;     __device__ __forceinline__ void operator()(const f32x4 (&acc)[2][2][4][2], const pg8::Unit& u, int wr, int wc, int fr, int fq) const {
;     ...
;                         const f32x4 v = gv[bj][n] * acc[ai][bj][m][n]; float* pe = rowp + bj * 128 + n * 16;
;                         if (split) *(f32x4*)(pe + pboff) = v;
;                         else { f32x4* p = (f32x4*)pe; *p = *p + v; }
	global_store_dwordx4 v153, v[68:71], s[4:5] offset:512
	s_waitcnt vmcnt(15)
	v_pk_add_f32 v[66:67], v[66:67], v[246:247]
	v_pk_add_f32 v[64:65], v[64:65], v[244:245]

;     __device__ __forceinline__ void operator()(const f32x4 (&acc)[2][2][4][2], const pg8::Unit& u, int wr, int wc, int fr, int fq) const {
;     ...
;                         const f32x4 v = gv[bj][n] * acc[ai][bj][m][n]; float* pe = rowp + bj * 128 + n * 16;
;                         if (split) *(f32x4*)(pe + pboff) = v;
;                         else { f32x4* p = (f32x4*)pe; *p = *p + v; }
	global_store_dwordx4 v153, v[64:67], s[4:5] offset:576
	global_load_dwordx4 v[162:165], v154, s[2:3]
	global_load_dwordx4 v[166:169], v154, s[2:3] offset:64
	global_load_dwordx4 v[170:173], v154, s[2:3] offset:512
	global_load_dwordx4 v[174:177], v154, s[2:3] offset:576
	global_load_dwordx4 v[184:187], v155, s[2:3]
	global_load_dwordx4 v[188:191], v155, s[2:3] offset:64
	global_load_dwordx4 v[204:207], v155, s[2:3] offset:512
	global_load_dwordx4 v[210:213], v155, s[2:3] offset:576
	global_load_dwordx4 v[214:217], v156, s[2:3]
	global_load_dwordx4 v[218:221], v156, s[2:3] offset:64
	global_load_dwordx4 v[222:225], v156, s[2:3] offset:512
	global_load_dwordx4 v[228:231], v156, s[2:3] offset:576
	global_load_dwordx4 v[232:235], v157, s[2:3]
	global_load_dwordx4 v[236:239], v157, s[2:3] offset:64
	global_load_dwordx4 v[240:243], v157, s[2:3] offset:512
	global_load_dwordx4 v[244:247], v157, s[2:3] offset:576
	s_waitcnt vmcnt(15)
	v_pk_add_f32 v[62:63], v[62:63], v[164:165]
	v_pk_add_f32 v[60:61], v[60:61], v[162:163]

;     __device__ __forceinline__ void operator()(const f32x4 (&acc)[2][2][4][2], const pg8::Unit& u, int wr, int wc, int fr, int fq) const {
;     ...
;                         const f32x4 v = gv[bj][n] * acc[ai][bj][m][n]; float* pe = rowp + bj * 128 + n * 16;
;                         if (split) *(f32x4*)(pe + pboff) = v;
;                         else { f32x4* p = (f32x4*)pe; *p = *p + v; }
	global_store_dwordx4 v154, v[60:63], s[4:5]
	s_waitcnt vmcnt(15)
	v_pk_add_f32 v[58:59], v[58:59], v[168:169]
	v_pk_add_f32 v[56:57], v[56:57], v[166:167]

;     __device__ __forceinline__ void operator()(const f32x4 (&acc)[2][2][4][2], const pg8::Unit& u, int wr, int wc, int fr, int fq) const {
;     ...
;                         const f32x4 v = gv[bj][n] * acc[ai][bj][m][n]; float* pe = rowp + bj * 128 + n * 16;
;                         if (split) *(f32x4*)(pe + pboff) = v;
;                         else { f32x4* p = (f32x4*)pe; *p = *p + v; }
	global_store_dwordx4 v154, v[56:59], s[4:5] offset:64
	s_waitcnt vmcnt(15)
	v_pk_add_f32 v[54:55], v[54:55], v[172:173]
	v_pk_add_f32 v[52:53], v[52:53], v[170:171]

;     __device__ __forceinline__ void operator()(const f32x4 (&acc)[2][2][4][2], const pg8::Unit& u, int wr, int wc, int fr, int fq) const {
;     ...
;                         const f32x4 v = gv[bj][n] * acc[ai][bj][m][n]; float* pe = rowp + bj * 128 + n * 16;
;                         if (split) *(f32x4*)(pe + pboff) = v;
;                         else { f32x4* p = (f32x4*)pe; *p = *p + v; }
	global_store_dwordx4 v154, v[52:55], s[4:5] offset:512
	s_waitcnt vmcnt(15)
	v_pk_add_f32 v[50:51], v[50:51], v[176:177]
	v_pk_add_f32 v[48:49], v[48:49], v[174:175]

;     __device__ __forceinline__ void operator()(const f32x4 (&acc)[2][2][4][2], const pg8::Unit& u, int wr, int wc, int fr, int fq) const {
;     ...
;                         const f32x4 v = gv[bj][n] * acc[ai][bj][m][n]; float* pe = rowp + bj * 128 + n * 16;
;                         if (split) *(f32x4*)(pe + pboff) = v;
;                         else { f32x4* p = (f32x4*)pe; *p = *p + v; }
	global_store_dwordx4 v154, v[48:51], s[4:5] offset:576
	s_waitcnt vmcnt(15)
	v_pk_add_f32 v[46:47], v[46:47], v[186:187]
	v_pk_add_f32 v[44:45], v[44:45], v[184:185]

;     __device__ __forceinline__ void operator()(const f32x4 (&acc)[2][2][4][2], const pg8::Unit& u, int wr, int wc, int fr, int fq) const {
;     ...
;                         const f32x4 v = gv[bj][n] * acc[ai][bj][m][n]; float* pe = rowp + bj * 128 + n * 16;
;                         if (split) *(f32x4*)(pe + pboff) = v;
;                         else { f32x4* p = (f32x4*)pe; *p = *p + v; }
	global_store_dwordx4 v155, v[44:47], s[4:5]
	s_waitcnt vmcnt(15)
	v_pk_add_f32 v[42:43], v[42:43], v[190:191]
	v_pk_add_f32 v[40:41], v[40:41], v[188:189]

;     __device__ __forceinline__ void operator()(const f32x4 (&acc)[2][2][4][2], const pg8::Unit& u, int wr, int wc, int fr, int fq) const {
;     ...
;                         const f32x4 v = gv[bj][n] * acc[ai][bj][m][n]; float* pe = rowp + bj * 128 + n * 16;
;                         if (split) *(f32x4*)(pe + pboff) = v;
;                         else { f32x4* p = (f32x4*)pe; *p = *p + v; }
	global_store_dwordx4 v155, v[40:43], s[4:5] offset:64
	s_waitcnt vmcnt(15)
	v_pk_add_f32 v[38:39], v[38:39], v[206:207]
	v_pk_add_f32 v[36:37], v[36:37], v[204:205]

;     __device__ __forceinline__ void operator()(const f32x4 (&acc)[2][2][4][2], const pg8::Unit& u, int wr, int wc, int fr, int fq) const {
;     ...
;                         const f32x4 v = gv[bj][n] * acc[ai][bj][m][n]; float* pe = rowp + bj * 128 + n * 16;
;                         if (split) *(f32x4*)(pe + pboff) = v;
;                         else { f32x4* p = (f32x4*)pe; *p = *p + v; }
	global_store_dwordx4 v155, v[36:39], s[4:5] offset:512
	s_waitcnt vmcnt(15)
	v_pk_add_f32 v[34:35], v[34:35], v[212:213]
	v_pk_add_f32 v[32:33], v[32:33], v[210:211]

;     __device__ __forceinline__ void operator()(const f32x4 (&acc)[2][2][4][2], const pg8::Unit& u, int wr, int wc, int fr, int fq) const {
;     ...
;                         const f32x4 v = gv[bj][n] * acc[ai][bj][m][n]; float* pe = rowp + bj * 128 + n * 16;
;                         if (split) *(f32x4*)(pe + pboff) = v;
;                         else { f32x4* p = (f32x4*)pe; *p = *p + v; }
	global_store_dwordx4 v155, v[32:35], s[4:5] offset:576
	s_waitcnt vmcnt(15)
	v_pk_add_f32 v[30:31], v[30:31], v[216:217]
	v_pk_add_f32 v[28:29], v[28:29], v[214:215]

;     __device__ __forceinline__ void operator()(const f32x4 (&acc)[2][2][4][2], const pg8::Unit& u, int wr, int wc, int fr, int fq) const {
;     ...
;                         const f32x4 v = gv[bj][n] * acc[ai][bj][m][n]; float* pe = rowp + bj * 128 + n * 16;
;                         if (split) *(f32x4*)(pe + pboff) = v;
;                         else { f32x4* p = (f32x4*)pe; *p = *p + v; }
	global_store_dwordx4 v156, v[28:31], s[4:5]
	s_waitcnt vmcnt(15)
	v_pk_add_f32 v[26:27], v[26:27], v[220:221]
	v_pk_add_f32 v[24:25], v[24:25], v[218:219]

;     __device__ __forceinline__ void operator()(const f32x4 (&acc)[2][2][4][2], const pg8::Unit& u, int wr, int wc, int fr, int fq) const {
;     ...
;                         const f32x4 v = gv[bj][n] * acc[ai][bj][m][n]; float* pe = rowp + bj * 128 + n * 16;
;                         if (split) *(f32x4*)(pe + pboff) = v;
;                         else { f32x4* p = (f32x4*)pe; *p = *p + v; }
	global_store_dwordx4 v156, v[24:27], s[4:5] offset:64
	s_waitcnt vmcnt(15)
	v_pk_add_f32 v[22:23], v[22:23], v[224:225]
	v_pk_add_f32 v[20:21], v[20:21], v[222:223]

;     __device__ __forceinline__ void operator()(const f32x4 (&acc)[2][2][4][2], const pg8::Unit& u, int wr, int wc, int fr, int fq) const {
;     ...
;                         const f32x4 v = gv[bj][n] * acc[ai][bj][m][n]; float* pe = rowp + bj * 128 + n * 16;
;                         if (split) *(f32x4*)(pe + pboff) = v;
;                         else { f32x4* p = (f32x4*)pe; *p = *p + v; }
	global_store_dwordx4 v156, v[20:23], s[4:5] offset:512
	s_waitcnt vmcnt(15)
	v_pk_add_f32 v[18:19], v[18:19], v[230:231]
	v_pk_add_f32 v[16:17], v[16:17], v[228:229]

;     __device__ __forceinline__ void operator()(const f32x4 (&acc)[2][2][4][2], const pg8::Unit& u, int wr, int wc, int fr, int fq) const {
;     ...
;                         const f32x4 v = gv[bj][n] * acc[ai][bj][m][n]; float* pe = rowp + bj * 128 + n * 16;
;                         if (split) *(f32x4*)(pe + pboff) = v;
;                         else { f32x4* p = (f32x4*)pe; *p = *p + v; }
	global_store_dwordx4 v156, v[16:19], s[4:5] offset:576
	s_waitcnt vmcnt(15)
	v_pk_add_f32 v[14:15], v[14:15], v[234:235]
	v_pk_add_f32 v[12:13], v[12:13], v[232:233]

;     __device__ __forceinline__ void operator()(const f32x4 (&acc)[2][2][4][2], const pg8::Unit& u, int wr, int wc, int fr, int fq) const {
;     ...
;                         const f32x4 v = gv[bj][n] * acc[ai][bj][m][n]; float* pe = rowp + bj * 128 + n * 16;
;                         if (split) *(f32x4*)(pe + pboff) = v;
;                         else { f32x4* p = (f32x4*)pe; *p = *p + v; }
	global_store_dwordx4 v157, v[12:15], s[4:5]
	s_waitcnt vmcnt(15)
	v_pk_add_f32 v[10:11], v[10:11], v[238:239]
	v_pk_add_f32 v[8:9], v[8:9], v[236:237]

;     __device__ __forceinline__ void operator()(const f32x4 (&acc)[2][2][4][2], const pg8::Unit& u, int wr, int wc, int fr, int fq) const {
;     ...
;                         const f32x4 v = gv[bj][n] * acc[ai][bj][m][n]; float* pe = rowp + bj * 128 + n * 16;
;                         if (split) *(f32x4*)(pe + pboff) = v;
;                         else { f32x4* p = (f32x4*)pe; *p = *p + v; }
	global_store_dwordx4 v157, v[8:11], s[4:5] offset:64
	s_waitcnt vmcnt(15)
	v_pk_add_f32 v[6:7], v[6:7], v[242:243]
	v_pk_add_f32 v[4:5], v[4:5], v[240:241]

;     __device__ __forceinline__ void operator()(const f32x4 (&acc)[2][2][4][2], const pg8::Unit& u, int wr, int wc, int fr, int fq) const {
;     ...
;                         const f32x4 v = gv[bj][n] * acc[ai][bj][m][n]; float* pe = rowp + bj * 128 + n * 16;
;                         if (split) *(f32x4*)(pe + pboff) = v;
;                         else { f32x4* p = (f32x4*)pe; *p = *p + v; }
	global_store_dwordx4 v157, v[4:7], s[4:5] offset:512
	s_waitcnt vmcnt(15)
	v_pk_add_f32 v[2:3], v[2:3], v[246:247]
	v_pk_add_f32 v[0:1], v[0:1], v[244:245]

;     __device__ __forceinline__ void operator()(const f32x4 (&acc)[2][2][4][2], const pg8::Unit& u, int wr, int wc, int fr, int fq) const {
;     ...
;                         const f32x4 v = gv[bj][n] * acc[ai][bj][m][n]; float* pe = rowp + bj * 128 + n * 16;
;                         if (split) *(f32x4*)(pe + pboff) = v;
;                         else { f32x4* p = (f32x4*)pe; *p = *p + v; }
	global_store_dwordx4 v157, v[0:3], s[4:5] offset:576

; __device__ __forceinline__ void ph_cvt_norm1(unsigned char* smem, int li) {
;     ...
;     for (int row = gw; row < MT; row += NGW) {
;         const int mi = row < ML ? row >> 11 : 8;
;         if (row < ML || li == 0) { float* xr = row < ML ? XL + (size_t)row * DM : XC + (size_t)(row - ML) * DM; mod_row<0>(xr, nullptr, g1, md + mi * 6144, md + mi * 6144 + 1024, H + (size_t)row * DM, lane); }
.LBB0_1085:
	s_cmpk_gt_i32 s18, 0x47ff
	s_cbranch_scc1 .LBB0_1094
	s_lshl_b32 s2, s33, 1
	v_readlane_b32 s6, v255, 10
	s_ashr_i32 s3, s2, 31
	s_add_i32 s6, s6, 8
	s_lshl_b64 s[2:3], s[2:3], 12
	s_and_b32 s6, s6, 0xff
	s_cmp_lt_u32 s6, 17
	s_cselect_b64 s[16:17], -1, 0
	s_waitcnt lgkmcnt(0)
	s_add_u32 s44, s42, 0x2200000
	s_addc_u32 s45, s43, 0
	s_add_u32 s6, s42, 0x2c00000
	s_mul_i32 s5, s33, 0x36000
	s_addc_u32 s7, s43, 0
	s_load_dwordx2 s[8:9], s[48:49], 0x30
	s_mul_hi_i32 s4, s33, 0x36000
	s_add_u32 s5, s42, s5
	s_addc_u32 s19, s43, s4
	s_add_u32 s4, s5, 0x2a00000
	s_addc_u32 s5, s19, 0
	s_waitcnt lgkmcnt(0)
	s_cmp_lg_u32 s29, 1
	s_cbranch_scc1 .Ln1_keep_out
	s_load_dwordx2 s[40:41], s[48:49], 0x0
	s_waitcnt lgkmcnt(0)

; template <int NP> __device__ __forceinline__ void mod_row(float* xrow, const float* prow, const float* g, const float* sh, const float* sc, bf16_t* orow, int lane) {
;     f32x4 v[4]; float s = 0.f;
; #pragma unroll
;     for (int j = 0; j < 4; ++j) { v[j] = *(const f32x4*)(xrow + 4 * lane + 256 * j);
; __device__ __forceinline__ void ph_cvt_norm1(unsigned char* smem, int li) {
;     ...
;     for (int row = gw; row < MT; row += NGW) {
;         const int mi = row < ML ? row >> 11 : 8;
;         if (row < ML || li == 0) { float* xr = row < ML ? XL + (size_t)row * DM : XC + (size_t)(row - ML) * DM; mod_row<0>(xr, nullptr, g1, md + mi * 6144, md + mi * 6144 + 1024, H + (size_t)row * DM, lane); }
;         else mod_row<4>(XC + (size_t)(row - ML) * DM, (const float*)(R + 108 * MiB) + (size_t)(row - ML) * DM, g1, md + mi * 6144, md + mi * 6144 + 1024, H + (size_t)row * DM, lane);
.Ln1_keep_out:
	s_add_u32 s2, s8, s2
	s_addc_u32 s3, s9, s3
	v_lshlrev_b32_e32 v2, 2, v5
	v_lshlrev_b32_e32 v180, 4, v5
	s_ashr_i32 s19, s18, 31
	v_lshl_add_u64 v[8:9], s[2:3], 0, v[180:181]
	v_or_b32_e32 v14, 0x300, v2
	s_ashr_i32 s39, s38, 31
	s_lshl_b64 s[2:3], s[18:19], 12
	v_lshl_add_u64 v[4:5], s[44:45], 0, v[180:181]
	v_lshl_add_u64 v[6:7], s[42:43], 0, v[180:181]
	s_mov_b64 s[8:9], 0xbc00000
	v_mov_b32_e32 v1, v181
	v_lshlrev_b32_e32 v180, 1, v14
	s_add_u32 s40, s40, s2
	v_lshl_add_u64 v[6:7], v[6:7], 0, s[8:9]
	v_xor_b32_e32 v3, 4, v2
	v_xor_b32_e32 v11, 8, v2
	v_xor_b32_e32 v13, 16, v2
	v_xor_b32_e32 v15, 32, v2
	v_xor_b32_e32 v20, 64, v2
	v_xor_b32_e32 v21, 0x80, v2
	v_or_b32_e32 v10, 0x100, v2
	v_or_b32_e32 v12, 0x200, v2
	v_lshl_add_u64 v[0:1], s[6:7], 0, v[0:1]
	v_lshl_add_u64 v[16:17], s[6:7], 0, v[180:181]
	s_addc_u32 s41, s41, s3
	s_lshl_b64 s[42:43], s[38:39], 12
	s_branch .LBB0_1089

; __device__ __forceinline__ void ph_prologue(unsigned char* smem) {
;     ...
;     const size_t gt = (size_t)bid * 512 + tid, NT = (size_t)G * 512;
;     for (size_t i = gt; i < (size_t)ML * DM / 4; i += NT) ((f32x4*)XL)[i] = ((const f32x4*)p.x)[i];
;     for (size_t i = gt; i < (size_t)MC * DM / 4; i += NT) ((f32x4*)XC)[i] = ((const f32x4*)p.ctx)[i];
.LBB0_1096:
	s_mov_b64 s[16:17], s[90:91]
	s_waitcnt vmcnt(0)
	s_barrier
	s_load_dwordx4 s[40:43], s[16:17], 0xa0
	v_mov_b32_e32 v0, v194
	s_mov_b32 s18, s94
	s_mov_b32 s44, s89
	s_ashr_i32 s45, s44, 31
	s_lshl_b64 s[2:3], s[44:45], 9
	v_ashrrev_i32_e32 v1, 31, v0
	v_lshl_add_u64 v[2:3], s[2:3], 0, v[0:1]
	s_ashr_i32 s19, s18, 31
	s_lshl_b64 s[38:39], s[18:19], 9
	s_cmp_lg_u32 s18, 0x100
	s_cbranch_scc1 .Lp0_generic_copy
	s_load_dwordx2 s[46:47], s[16:17], 0x0
	s_load_dwordx2 s[48:49], s[16:17], 0x10
	v_lshlrev_b32_e32 v4, 4, v2
	s_waitcnt lgkmcnt(0)
	s_mov_b64 s[2:3], s[46:47]
	s_mov_b64 s[4:5], s[40:41]
	s_mov_b32 s50, 2

; __device__ __forceinline__ void ph_prologue(unsigned char* smem) {
;     ...
;     for (size_t i = gt; i < (size_t)ML * DM / 4; i += NT) ((f32x4*)XL)[i] = ((const f32x4*)p.x)[i];
;     for (size_t i = gt; i < (size_t)MC * DM / 4; i += NT) ((f32x4*)XC)[i] = ((const f32x4*)p.ctx)[i];
	s_mov_b64 s[2:3], s[48:49]
	s_add_u32 s4, s42, 0x2200000
	s_addc_u32 s5, s43, 0

; __device__ __forceinline__ void ph_prologue(unsigned char* smem) {
;     ...
;     for (size_t i = gt; i < (size_t)MC * DM / 4; i += NT) ((f32x4*)XC)[i] = ((const f32x4*)p.ctx)[i];
	global_load_dwordx4 v[8:11], v4, s[2:3]
	s_add_u32 s2, s2, 0x200000
	s_addc_u32 s3, s3, 0

; __device__ __forceinline__ void ph_prologue(unsigned char* smem) {
;     ...
;     for (size_t i = gt; i < (size_t)MC * DM / 4; i += NT) ((f32x4*)XC)[i] = ((const f32x4*)p.ctx)[i];
	global_load_dwordx4 v[12:15], v4, s[2:3]
	s_add_u32 s2, s2, 0x200000
	s_addc_u32 s3, s3, 0

; __device__ __forceinline__ void ph_prologue(unsigned char* smem) {
;     ...
;     for (size_t i = gt; i < (size_t)MC * DM / 4; i += NT) ((f32x4*)XC)[i] = ((const f32x4*)p.ctx)[i];
	global_load_dwordx4 v[16:19], v4, s[2:3]
	s_add_u32 s2, s2, 0x200000
	s_addc_u32 s3, s3, 0

; __device__ __forceinline__ void ph_prologue(unsigned char* smem) {
;     ...
;     for (size_t i = gt; i < (size_t)MC * DM / 4; i += NT) ((f32x4*)XC)[i] = ((const f32x4*)p.ctx)[i];
	global_load_dwordx4 v[20:23], v4, s[2:3]
	s_add_u32 s2, s2, 0x200000
	s_addc_u32 s3, s3, 0

; __device__ __forceinline__ void ph_prologue(unsigned char* smem) {
;     ...
;     for (size_t i = gt; i < (size_t)MC * DM / 4; i += NT) ((f32x4*)XC)[i] = ((const f32x4*)p.ctx)[i];
	s_waitcnt vmcnt(3)
	global_store_dwordx4 v4, v[8:11], s[4:5]
	s_add_u32 s4, s4, 0x200000
	s_addc_u32 s5, s5, 0

; __device__ __forceinline__ void ph_prologue(unsigned char* smem) {
;     ...
;     for (size_t i = gt; i < (size_t)MC * DM / 4; i += NT) ((f32x4*)XC)[i] = ((const f32x4*)p.ctx)[i];
	s_waitcnt vmcnt(3)
	global_store_dwordx4 v4, v[12:15], s[4:5]
	s_add_u32 s4, s4, 0x200000
	s_addc_u32 s5, s5, 0

; __device__ __forceinline__ void ph_prologue(unsigned char* smem) {
;     ...
;     for (size_t i = gt; i < (size_t)MC * DM / 4; i += NT) ((f32x4*)XC)[i] = ((const f32x4*)p.ctx)[i];
	s_waitcnt vmcnt(3)
	global_store_dwordx4 v4, v[16:19], s[4:5]
	s_add_u32 s4, s4, 0x200000
	s_addc_u32 s5, s5, 0

; __device__ __forceinline__ void ph_prologue(unsigned char* smem) {
;     ...
;     for (size_t i = gt; i < (size_t)MC * DM / 4; i += NT) ((f32x4*)XC)[i] = ((const f32x4*)p.ctx)[i];
	s_waitcnt vmcnt(3)
	global_store_dwordx4 v4, v[20:23], s[4:5]
	s_add_u32 s4, s4, 0x200000
	s_addc_u32 s5, s5, 0

; __device__ __forceinline__ void ph_prologue(unsigned char* smem) {
;     ...
;     const size_t gt = (size_t)bid * 512 + tid, NT = (size_t)G * 512;
;     for (size_t i = gt; i < (size_t)ML * DM / 4; i += NT) ((f32x4*)XL)[i] = ((const f32x4*)p.x)[i];
;     for (size_t i = gt; i < (size_t)MC * DM / 4; i += NT) ((f32x4*)XC)[i] = ((const f32x4*)p.ctx)[i];
	s_branch .LBB0_1102

